# v77 + global barriers at layer boundaries and before each XQ phase (2 resyncs per layer)
# baseline (speedup 1.0000x reference)
; #define LAS __attribute__((address_space(3)))
; __device__ __forceinline__ unsigned xb_xcc_id() { return (unsigned)__builtin_amdgcn_s_getreg((3 << 11) | 20) & 0xFu; }
; __global__ void __launch_bounds__(NWAVES * 64, 2) trunk_fwd(Args args) {
;     ...
;         }
;         if (ph + 1 < ph_hi) { XcdBarrier xb_; xb_.bar = (unsigned*)ws; xb_.x = xb_xcc_id(); xb_.st = (volatile LAS unsigned*)(L + XB_ST_OFF); xcd_barrier(xb_); }
.LBB0_652:
	s_andn2_saveexec_b64 s[8:9], s[8:9]
	s_cbranch_execz .LBB0_169
	s_mov_b64 s[8:9], exec
	s_waitcnt lgkmcnt(0)
	v_readlane_b32 s0, v255, 9
	s_lshl_b32 s0, 1, s0
	s_and_b32 s0, s0, 0x1dbb76e8
	s_cbranch_scc0 .Lxb_global
	v_readlane_b32 s0, v255, 42
	s_cmp_eq_u32 s0, 0
	s_cbranch_scc1 .Lxb_local
